# P2a conv prefetch with the mid-loop vmcnt(0) removed (rows arrive via the prefetch registers)
# speedup vs baseline: 1.0057x; 1.0026x over previous
; __device__ __forceinline__ unsigned pk2(float lo, float hi) { f32x2_c v = {lo, hi}; return __builtin_bit_cast(unsigned, __builtin_convertvector(v, bf16x2_c)); }
; __device__ __forceinline__ float bf2f(unsigned short h) { return __uint_as_float(((unsigned)h) << 16); }
; __device__ __forceinline__ float silu_f(float x) { return x * __builtin_amdgcn_rcpf(1.f + __expf(-x)); }
; __device__ __forceinline__ void p2a_conv(const Args& A, int G) {
;     ...
;         for (int i0 = 0; i0 < 32; i0 += 8) { bf16x8 rr[8];
; #pragma unroll
;         for (int i = 0; i < 8; ++i) rr[i] = *(const bf16x8*)(P0 + (size_t)(m0 + i0 + i) * LD0 + C0_XBC + ch);
; #pragma unroll
;         for (int ii = 0; ii < 8; ++ii) { const int i = i0 + ii; const bf16x8 r3 = rr[ii]; float o[8];
; #pragma unroll
;             for (int e = 0; e < 8; ++e) { const float a = bs[e] + w[0][e] * bf2f((unsigned short)r0[e]) + w[1][e] * bf2f((unsigned short)r1[e]) + w[2][e] * bf2f((unsigned short)r2[e]) + w[3][e] * bf2f((unsigned short)r3[e]); o[e] = silu_f(a); }
;             v4u pw; pw.x = pk2(o[0], o[1]); pw.y = pk2(o[2], o[3]); pw.z = pk2(o[4], o[5]); pw.w = pk2(o[6], o[7]);
;             *(v4u*)(XC + (size_t)(m0 + i) * 2048 + ch) = pw; r0 = r1; r1 = r2; r2 = r3; } }
.Lcv_nopf:
	s_cmp_gt_u32 s4, 23
	s_waitcnt lgkmcnt(0)
	v_and_b32_e32 v85, 0xffff0000, v42
	v_lshlrev_b32_e32 v84, 16, v42
	v_and_b32_e32 v87, 0xffff0000, v43
	v_lshlrev_b32_e32 v86, 16, v43
	v_and_b32_e32 v43, 0xffff0000, v44
	v_lshlrev_b32_e32 v42, 16, v44
	v_and_b32_e32 v89, 0xffff0000, v45
	v_lshlrev_b32_e32 v88, 16, v45
	v_pk_fma_f32 v[76:77], v[24:25], v[84:85], v[130:131]
	v_pk_fma_f32 v[78:79], v[26:27], v[86:87], v[132:133]
	v_pk_fma_f32 v[80:81], v[28:29], v[42:43], v[134:135]
	v_pk_fma_f32 v[82:83], v[30:31], v[88:89], v[136:137]
	v_pk_fma_f32 v[44:45], v[16:17], v[84:85], v[90:91]
	v_and_b32_e32 v115, 0xffff0000, v46
	v_lshlrev_b32_e32 v114, 16, v46
	v_pk_fma_f32 v[90:91], v[18:19], v[86:87], v[120:121]
	v_and_b32_e32 v121, 0xffff0000, v47
	v_lshlrev_b32_e32 v120, 16, v47
	v_pk_fma_f32 v[46:47], v[20:21], v[42:43], v[122:123]
	v_and_b32_e32 v123, 0xffff0000, v48
	v_lshlrev_b32_e32 v122, 16, v48
	v_pk_fma_f32 v[96:97], v[22:23], v[88:89], v[96:97]
	v_and_b32_e32 v131, 0xffff0000, v49
	v_lshlrev_b32_e32 v130, 16, v49
	v_pk_fma_f32 v[48:49], v[8:9], v[84:85], v[98:99]
	v_pk_fma_f32 v[98:99], v[10:11], v[86:87], v[104:105]
	v_pk_fma_f32 v[104:105], v[12:13], v[42:43], v[106:107]
	v_pk_fma_f32 v[106:107], v[14:15], v[88:89], v[112:113]
	v_pk_fma_f32 v[112:113], v[0:1], v[84:85], v[32:33]
	v_pk_fma_f32 v[132:133], v[2:3], v[86:87], v[34:35]
	v_pk_fma_f32 v[42:43], v[4:5], v[42:43], v[36:37]
	v_pk_fma_f32 v[134:135], v[6:7], v[88:89], v[38:39]
	v_mul_f32_e32 v41, 0xbfb8aa3b, v76
	v_mul_f32_e32 v138, 0xbfb8aa3b, v77
	v_mul_f32_e32 v139, 0xbfb8aa3b, v78
	v_mul_f32_e32 v140, 0xbfb8aa3b, v79
	v_mul_f32_e32 v141, 0xbfb8aa3b, v80
	v_mul_f32_e32 v142, 0xbfb8aa3b, v81
	v_mul_f32_e32 v143, 0xbfb8aa3b, v82
	v_mul_f32_e32 v144, 0xbfb8aa3b, v83
	v_pk_fma_f32 v[84:85], v[24:25], v[114:115], v[44:45]
	v_pk_fma_f32 v[86:87], v[26:27], v[120:121], v[90:91]
	v_pk_fma_f32 v[88:89], v[28:29], v[122:123], v[46:47]
	v_pk_fma_f32 v[90:91], v[30:31], v[130:131], v[96:97]
	v_pk_fma_f32 v[44:45], v[16:17], v[114:115], v[48:49]
	v_and_b32_e32 v47, 0xffff0000, v92
	v_lshlrev_b32_e32 v46, 16, v92
	v_pk_fma_f32 v[48:49], v[18:19], v[120:121], v[98:99]
	v_and_b32_e32 v137, 0xffff0000, v93
	v_lshlrev_b32_e32 v136, 16, v93
	v_pk_fma_f32 v[96:97], v[20:21], v[122:123], v[104:105]
	v_and_b32_e32 v105, 0xffff0000, v94
	v_lshlrev_b32_e32 v104, 16, v94
	v_pk_fma_f32 v[98:99], v[22:23], v[130:131], v[106:107]
	v_and_b32_e32 v107, 0xffff0000, v95
	v_lshlrev_b32_e32 v106, 16, v95
	v_pk_fma_f32 v[112:113], v[8:9], v[114:115], v[112:113]
	v_pk_fma_f32 v[132:133], v[10:11], v[120:121], v[132:133]
	v_pk_fma_f32 v[42:43], v[12:13], v[122:123], v[42:43]
	v_pk_fma_f32 v[134:135], v[14:15], v[130:131], v[134:135]
	v_pk_fma_f32 v[114:115], v[0:1], v[114:115], v[32:33]
	v_pk_fma_f32 v[120:121], v[2:3], v[120:121], v[34:35]
	v_pk_fma_f32 v[122:123], v[4:5], v[122:123], v[36:37]
	v_pk_fma_f32 v[130:131], v[6:7], v[130:131], v[38:39]
	v_exp_f32_e32 v41, v41
	v_exp_f32_e32 v162, v138
	v_exp_f32_e32 v163, v139
	v_exp_f32_e32 v164, v140
	v_exp_f32_e32 v165, v141
	v_exp_f32_e32 v166, v142
	v_exp_f32_e32 v167, v143
	v_exp_f32_e32 v168, v144
	v_mul_f32_e32 v146, 0xbfb8aa3b, v84
	v_mul_f32_e32 v147, 0xbfb8aa3b, v85
	v_mul_f32_e32 v148, 0xbfb8aa3b, v86
	v_mul_f32_e32 v149, 0xbfb8aa3b, v87
	v_mul_f32_e32 v150, 0xbfb8aa3b, v88
	v_mul_f32_e32 v151, 0xbfb8aa3b, v89
	v_mul_f32_e32 v152, 0xbfb8aa3b, v90
	v_mul_f32_e32 v153, 0xbfb8aa3b, v91
	v_pk_fma_f32 v[92:93], v[24:25], v[46:47], v[44:45]
	v_pk_fma_f32 v[94:95], v[26:27], v[136:137], v[48:49]
	v_pk_fma_f32 v[96:97], v[28:29], v[104:105], v[96:97]
	v_pk_fma_f32 v[98:99], v[30:31], v[106:107], v[98:99]
	v_pk_fma_f32 v[44:45], v[16:17], v[46:47], v[112:113]
	v_and_b32_e32 v49, 0xffff0000, v100
	v_lshlrev_b32_e32 v48, 16, v100
	v_pk_fma_f32 v[112:113], v[18:19], v[136:137], v[132:133]
	v_and_b32_e32 v133, 0xffff0000, v101
	v_lshlrev_b32_e32 v132, 16, v101
	v_pk_fma_f32 v[42:43], v[20:21], v[104:105], v[42:43]
	v_and_b32_e32 v139, 0xffff0000, v102
	v_lshlrev_b32_e32 v138, 16, v102
	v_pk_fma_f32 v[134:135], v[22:23], v[106:107], v[134:135]
	v_and_b32_e32 v141, 0xffff0000, v103
	v_lshlrev_b32_e32 v140, 16, v103
	v_pk_fma_f32 v[114:115], v[8:9], v[46:47], v[114:115]
	v_pk_fma_f32 v[120:121], v[10:11], v[136:137], v[120:121]
	v_pk_fma_f32 v[122:123], v[12:13], v[104:105], v[122:123]
	v_pk_fma_f32 v[130:131], v[14:15], v[106:107], v[130:131]
	v_pk_fma_f32 v[46:47], v[0:1], v[46:47], v[32:33]
	v_pk_fma_f32 v[136:137], v[2:3], v[136:137], v[34:35]
	v_pk_fma_f32 v[142:143], v[4:5], v[104:105], v[36:37]
	v_pk_fma_f32 v[144:145], v[6:7], v[106:107], v[38:39]
	v_exp_f32_e32 v169, v146
	v_exp_f32_e32 v170, v147
	v_exp_f32_e32 v171, v148
	v_exp_f32_e32 v172, v149
	v_exp_f32_e32 v173, v150
	v_exp_f32_e32 v174, v151
	v_exp_f32_e32 v175, v152
	v_exp_f32_e32 v176, v153
	v_mul_f32_e32 v146, 0xbfb8aa3b, v92
	v_mul_f32_e32 v147, 0xbfb8aa3b, v93
	v_mul_f32_e32 v148, 0xbfb8aa3b, v94
	v_mul_f32_e32 v149, 0xbfb8aa3b, v95
	v_mul_f32_e32 v150, 0xbfb8aa3b, v96
	v_mul_f32_e32 v151, 0xbfb8aa3b, v97
	v_mul_f32_e32 v152, 0xbfb8aa3b, v98
	v_mul_f32_e32 v153, 0xbfb8aa3b, v99
	v_pk_fma_f32 v[100:101], v[24:25], v[48:49], v[44:45]
	v_pk_fma_f32 v[102:103], v[26:27], v[132:133], v[112:113]
	v_pk_fma_f32 v[104:105], v[28:29], v[138:139], v[42:43]
	v_pk_fma_f32 v[106:107], v[30:31], v[140:141], v[134:135]
	v_pk_fma_f32 v[42:43], v[16:17], v[48:49], v[114:115]
	v_and_b32_e32 v45, 0xffff0000, v108
	v_lshlrev_b32_e32 v44, 16, v108
	v_pk_fma_f32 v[112:113], v[18:19], v[132:133], v[120:121]
	v_and_b32_e32 v121, 0xffff0000, v109
	v_lshlrev_b32_e32 v120, 16, v109
; __device__ __forceinline__ float bf2f(unsigned short h) { return __uint_as_float(((unsigned)h) << 16); }
; __device__ __forceinline__ float silu_f(float x) { return x * __builtin_amdgcn_rcpf(1.f + __expf(-x)); }
; __device__ __forceinline__ void p2a_conv(const Args& A, int G) {
;     ...
;         for (int ii = 0; ii < 8; ++ii) { const int i = i0 + ii; const bf16x8 r3 = rr[ii]; float o[8];
; #pragma unroll
;             for (int e = 0; e < 8; ++e) { const float a = bs[e] + w[0][e] * bf2f((unsigned short)r0[e]) + w[1][e] * bf2f((unsigned short)r1[e]) + w[2][e] * bf2f((unsigned short)r2[e]) + w[3][e] * bf2f((unsigned short)r3[e]); o[e] = silu_f(a); }
	v_pk_fma_f32 v[114:115], v[20:21], v[138:139], v[122:123]
	v_and_b32_e32 v123, 0xffff0000, v110
	v_lshlrev_b32_e32 v122, 16, v110
	v_pk_fma_f32 v[130:131], v[22:23], v[140:141], v[130:131]
	v_and_b32_e32 v135, 0xffff0000, v111
	v_lshlrev_b32_e32 v134, 16, v111
	v_pk_fma_f32 v[46:47], v[8:9], v[48:49], v[46:47]
	v_pk_fma_f32 v[136:137], v[10:11], v[132:133], v[136:137]
	v_pk_fma_f32 v[142:143], v[12:13], v[138:139], v[142:143]
	v_pk_fma_f32 v[144:145], v[14:15], v[140:141], v[144:145]
	v_pk_fma_f32 v[48:49], v[0:1], v[48:49], v[32:33]
	v_pk_fma_f32 v[132:133], v[2:3], v[132:133], v[34:35]
	v_pk_fma_f32 v[138:139], v[4:5], v[138:139], v[36:37]
	v_pk_fma_f32 v[140:141], v[6:7], v[140:141], v[38:39]
	v_exp_f32_e32 v177, v146
	v_exp_f32_e32 v178, v147
	v_exp_f32_e32 v179, v148
	v_exp_f32_e32 v180, v149
	v_exp_f32_e32 v181, v150
	v_exp_f32_e32 v182, v151
	v_exp_f32_e32 v183, v152
	v_exp_f32_e32 v184, v153
	v_mul_f32_e32 v158, 0xbfb8aa3b, v100
	v_mul_f32_e32 v159, 0xbfb8aa3b, v101
	v_mul_f32_e32 v160, 0xbfb8aa3b, v102
	v_mul_f32_e32 v161, 0xbfb8aa3b, v103
	v_mul_f32_e32 v185, 0xbfb8aa3b, v104
	v_mul_f32_e32 v186, 0xbfb8aa3b, v105
	v_mul_f32_e32 v187, 0xbfb8aa3b, v106
	v_mul_f32_e32 v188, 0xbfb8aa3b, v107
	v_pk_fma_f32 v[108:109], v[24:25], v[44:45], v[42:43]
	v_pk_fma_f32 v[110:111], v[26:27], v[120:121], v[112:113]
	v_pk_fma_f32 v[112:113], v[28:29], v[122:123], v[114:115]
	v_pk_fma_f32 v[114:115], v[30:31], v[134:135], v[130:131]
	v_pk_fma_f32 v[46:47], v[16:17], v[44:45], v[46:47]
	v_and_b32_e32 v131, 0xffff0000, v116
	v_lshlrev_b32_e32 v130, 16, v116
	v_pk_fma_f32 v[136:137], v[18:19], v[120:121], v[136:137]
	v_and_b32_e32 v147, 0xffff0000, v117
	v_lshlrev_b32_e32 v146, 16, v117
	v_pk_fma_f32 v[142:143], v[20:21], v[122:123], v[142:143]
	v_and_b32_e32 v149, 0xffff0000, v118
	v_lshlrev_b32_e32 v148, 16, v118
	v_pk_fma_f32 v[144:145], v[22:23], v[134:135], v[144:145]
	v_and_b32_e32 v151, 0xffff0000, v119
	v_lshlrev_b32_e32 v150, 16, v119
	v_pk_fma_f32 v[48:49], v[8:9], v[44:45], v[48:49]
	v_pk_fma_f32 v[132:133], v[10:11], v[120:121], v[132:133]
	v_pk_fma_f32 v[138:139], v[12:13], v[122:123], v[138:139]
	v_pk_fma_f32 v[140:141], v[14:15], v[134:135], v[140:141]
	v_pk_fma_f32 v[152:153], v[0:1], v[44:45], v[32:33]
	v_pk_fma_f32 v[154:155], v[2:3], v[120:121], v[34:35]
	v_pk_fma_f32 v[156:157], v[4:5], v[122:123], v[36:37]
	v_pk_fma_f32 v[134:135], v[6:7], v[134:135], v[38:39]
	v_mov_b64_e32 v[42:43], v[116:117]
	v_mov_b64_e32 v[44:45], v[118:119]
	v_exp_f32_e32 v189, v158
	v_exp_f32_e32 v190, v159
	v_exp_f32_e32 v191, v160
	v_exp_f32_e32 v192, v161
	v_exp_f32_e32 v185, v185
	v_exp_f32_e32 v186, v186
	v_exp_f32_e32 v187, v187
	v_exp_f32_e32 v188, v188
	v_mul_f32_e32 v193, 0xbfb8aa3b, v108
	v_mul_f32_e32 v194, 0xbfb8aa3b, v109
	v_mul_f32_e32 v195, 0xbfb8aa3b, v110
	v_mul_f32_e32 v196, 0xbfb8aa3b, v111
	v_mul_f32_e32 v197, 0xbfb8aa3b, v112
	v_mul_f32_e32 v198, 0xbfb8aa3b, v113
	v_mul_f32_e32 v199, 0xbfb8aa3b, v114
	v_mul_f32_e32 v200, 0xbfb8aa3b, v115
	v_pk_fma_f32 v[116:117], v[24:25], v[130:131], v[46:47]
	v_pk_fma_f32 v[118:119], v[26:27], v[146:147], v[136:137]
	v_pk_fma_f32 v[120:121], v[28:29], v[148:149], v[142:143]
	v_pk_fma_f32 v[122:123], v[30:31], v[150:151], v[144:145]
	v_pk_fma_f32 v[136:137], v[16:17], v[130:131], v[48:49]
	v_and_b32_e32 v143, 0xffff0000, v126
	v_lshlrev_b32_e32 v142, 16, v126
	v_pk_fma_f32 v[132:133], v[18:19], v[146:147], v[132:133]
	v_and_b32_e32 v145, 0xffff0000, v127
	v_lshlrev_b32_e32 v144, 16, v127
	v_pk_fma_f32 v[138:139], v[20:21], v[148:149], v[138:139]
	v_and_b32_e32 v159, 0xffff0000, v128
	v_lshlrev_b32_e32 v158, 16, v128
	v_pk_fma_f32 v[140:141], v[22:23], v[150:151], v[140:141]
	v_and_b32_e32 v161, 0xffff0000, v129
	v_lshlrev_b32_e32 v160, 16, v129
	v_pk_fma_f32 v[130:131], v[8:9], v[130:131], v[152:153]
	v_pk_fma_f32 v[146:147], v[10:11], v[146:147], v[154:155]
	v_pk_fma_f32 v[148:149], v[12:13], v[148:149], v[156:157]
	v_pk_fma_f32 v[134:135], v[14:15], v[150:151], v[134:135]
	v_mov_b64_e32 v[46:47], v[126:127]
	v_mov_b64_e32 v[48:49], v[128:129]
	v_add_f32_e32 v41, 1.0, v41
	v_add_f32_e32 v151, 1.0, v162
	v_add_f32_e32 v152, 1.0, v163
	v_add_f32_e32 v153, 1.0, v164
	v_add_f32_e32 v154, 1.0, v165
	v_add_f32_e32 v155, 1.0, v166
	v_add_f32_e32 v156, 1.0, v167
	v_add_f32_e32 v157, 1.0, v168
	v_exp_f32_e32 v193, v193
	v_exp_f32_e32 v194, v194
	v_exp_f32_e32 v195, v195
	v_exp_f32_e32 v196, v196
	v_exp_f32_e32 v197, v197
	v_exp_f32_e32 v198, v198
	v_exp_f32_e32 v199, v199
	v_exp_f32_e32 v200, v200
	v_mul_f32_e32 v162, 0xbfb8aa3b, v116
	v_mul_f32_e32 v163, 0xbfb8aa3b, v117
	v_mul_f32_e32 v164, 0xbfb8aa3b, v118
	v_mul_f32_e32 v165, 0xbfb8aa3b, v119
	v_mul_f32_e32 v166, 0xbfb8aa3b, v120
	v_mul_f32_e32 v167, 0xbfb8aa3b, v121
	v_mul_f32_e32 v168, 0xbfb8aa3b, v122
	v_mul_f32_e32 v201, 0xbfb8aa3b, v123
	v_pk_fma_f32 v[126:127], v[24:25], v[142:143], v[136:137]
	v_pk_fma_f32 v[128:129], v[26:27], v[144:145], v[132:133]
	v_pk_fma_f32 v[132:133], v[28:29], v[158:159], v[138:139]
	v_pk_fma_f32 v[136:137], v[30:31], v[160:161], v[140:141]
	v_pk_fma_f32 v[130:131], v[16:17], v[142:143], v[130:131]
	v_and_b32_e32 v139, 0xffff0000, v50
	v_lshlrev_b32_e32 v138, 16, v50
	v_pk_fma_f32 v[140:141], v[18:19], v[144:145], v[146:147]
	v_and_b32_e32 v143, 0xffff0000, v51
	v_lshlrev_b32_e32 v142, 16, v51
	v_pk_fma_f32 v[144:145], v[20:21], v[158:159], v[148:149]
	v_and_b32_e32 v147, 0xffff0000, v52
	v_lshlrev_b32_e32 v146, 16, v52
	v_pk_fma_f32 v[134:135], v[22:23], v[160:161], v[134:135]
	v_and_b32_e32 v149, 0xffff0000, v53
	v_lshlrev_b32_e32 v148, 16, v53
	v_rcp_f32_e32 v150, v41
	v_rcp_f32_e32 v151, v151
	v_rcp_f32_e32 v152, v152
; __device__ __forceinline__ unsigned pk2(float lo, float hi) { f32x2_c v = {lo, hi}; return __builtin_bit_cast(unsigned, __builtin_convertvector(v, bf16x2_c)); }
; __device__ __forceinline__ float bf2f(unsigned short h) { return __uint_as_float(((unsigned)h) << 16); }
; __device__ __forceinline__ float silu_f(float x) { return x * __builtin_amdgcn_rcpf(1.f + __expf(-x)); }
; __device__ __forceinline__ void p2a_conv(const Args& A, int G) {
;     ...
; #pragma unroll
;             for (int e = 0; e < 8; ++e) { const float a = bs[e] + w[0][e] * bf2f((unsigned short)r0[e]) + w[1][e] * bf2f((unsigned short)r1[e]) + w[2][e] * bf2f((unsigned short)r2[e]) + w[3][e] * bf2f((unsigned short)r3[e]); o[e] = silu_f(a); }
;             v4u pw; pw.x = pk2(o[0], o[1]); pw.y = pk2(o[2], o[3]); pw.z = pk2(o[4], o[5]); pw.w = pk2(o[6], o[7]);
	v_rcp_f32_e32 v153, v153
	v_rcp_f32_e32 v154, v154
	v_rcp_f32_e32 v155, v155
	v_rcp_f32_e32 v156, v156
	v_rcp_f32_e32 v157, v157
	v_add_f32_e32 v41, 1.0, v169
	v_add_f32_e32 v158, 1.0, v170
	v_add_f32_e32 v159, 1.0, v171
	v_add_f32_e32 v160, 1.0, v172
	v_add_f32_e32 v161, 1.0, v173
	v_add_f32_e32 v169, 1.0, v174
	v_add_f32_e32 v170, 1.0, v175
	v_add_f32_e32 v171, 1.0, v176
	v_exp_f32_e32 v174, v162
	v_exp_f32_e32 v175, v163
	v_exp_f32_e32 v176, v164
	v_exp_f32_e32 v202, v165
	v_exp_f32_e32 v203, v166
	v_exp_f32_e32 v204, v167
	v_exp_f32_e32 v205, v168
	v_exp_f32_e32 v201, v201
	v_mul_f32_e32 v162, 0xbfb8aa3b, v126
	v_mul_f32_e32 v163, 0xbfb8aa3b, v127
	v_mul_f32_e32 v164, 0xbfb8aa3b, v128
	v_mul_f32_e32 v165, 0xbfb8aa3b, v129
	v_mul_f32_e32 v166, 0xbfb8aa3b, v132
	v_mul_f32_e32 v167, 0xbfb8aa3b, v133
	v_mul_f32_e32 v168, 0xbfb8aa3b, v136
	v_mul_f32_e32 v172, 0xbfb8aa3b, v137
	v_pk_fma_f32 v[130:131], v[24:25], v[138:139], v[130:131]
	v_pk_fma_f32 v[138:139], v[26:27], v[142:143], v[140:141]
	v_pk_fma_f32 v[140:141], v[28:29], v[146:147], v[144:145]
	v_pk_fma_f32 v[134:135], v[30:31], v[148:149], v[134:135]
	v_rcp_f32_e32 v142, v41
	v_rcp_f32_e32 v143, v158
	v_rcp_f32_e32 v144, v159
	v_rcp_f32_e32 v145, v160
	v_rcp_f32_e32 v146, v161
	v_rcp_f32_e32 v147, v169
	v_rcp_f32_e32 v148, v170
	v_rcp_f32_e32 v149, v171
	v_add_f32_e32 v41, 1.0, v177
	v_add_f32_e32 v159, 1.0, v178
	v_add_f32_e32 v160, 1.0, v179
	v_add_f32_e32 v161, 1.0, v180
	v_add_f32_e32 v169, 1.0, v181
	v_add_f32_e32 v170, 1.0, v182
	v_add_f32_e32 v171, 1.0, v183
	v_add_f32_e32 v173, 1.0, v184
	v_exp_f32_e32 v177, v162
	v_exp_f32_e32 v178, v163
	v_exp_f32_e32 v179, v164
	v_exp_f32_e32 v180, v165
	v_exp_f32_e32 v181, v166
	v_exp_f32_e32 v182, v167
	v_exp_f32_e32 v183, v168
	v_exp_f32_e32 v184, v172
	v_mul_f32_e32 v166, 0xbfb8aa3b, v130
	v_mul_f32_e32 v167, 0xbfb8aa3b, v131
	v_mul_f32_e32 v168, 0xbfb8aa3b, v138
	v_mul_f32_e32 v172, 0xbfb8aa3b, v139
	v_mul_f32_e32 v206, 0xbfb8aa3b, v140
	v_mul_f32_e32 v207, 0xbfb8aa3b, v141
	v_mul_f32_e32 v208, 0xbfb8aa3b, v134
	v_mul_f32_e32 v209, 0xbfb8aa3b, v135
	v_rcp_f32_e32 v158, v41
	v_rcp_f32_e32 v159, v159
	v_rcp_f32_e32 v160, v160
	v_rcp_f32_e32 v161, v161
	v_rcp_f32_e32 v162, v169
	v_rcp_f32_e32 v163, v170
	v_rcp_f32_e32 v164, v171
	v_rcp_f32_e32 v165, v173
	v_add_f32_e32 v41, 1.0, v189
	v_add_f32_e32 v169, 1.0, v190
	v_add_f32_e32 v170, 1.0, v191
	v_add_f32_e32 v171, 1.0, v192
	v_add_f32_e32 v173, 1.0, v185
	v_add_f32_e32 v185, 1.0, v186
	v_add_f32_e32 v186, 1.0, v187
	v_add_f32_e32 v187, 1.0, v188
	v_exp_f32_e32 v188, v166
	v_exp_f32_e32 v189, v167
	v_exp_f32_e32 v190, v168
	v_exp_f32_e32 v191, v172
	v_exp_f32_e32 v192, v206
	v_exp_f32_e32 v206, v207
	v_exp_f32_e32 v207, v208
	v_exp_f32_e32 v208, v209
	v_rcp_f32_e32 v166, v41
	v_rcp_f32_e32 v167, v169
	v_rcp_f32_e32 v168, v170
	v_rcp_f32_e32 v169, v171
	v_rcp_f32_e32 v170, v173
	v_rcp_f32_e32 v171, v185
	v_rcp_f32_e32 v172, v186
	v_rcp_f32_e32 v173, v187
	v_add_f32_e32 v41, 1.0, v193
	v_add_f32_e32 v185, 1.0, v194
	v_add_f32_e32 v186, 1.0, v195
	v_add_f32_e32 v187, 1.0, v196
	v_add_f32_e32 v193, 1.0, v197
	v_add_f32_e32 v194, 1.0, v198
	v_add_f32_e32 v195, 1.0, v199
	v_add_f32_e32 v196, 1.0, v200
	v_pk_mul_f32 v[76:77], v[76:77], v[150:151]
	v_pk_mul_f32 v[78:79], v[78:79], v[152:153]
	v_pk_mul_f32 v[80:81], v[80:81], v[154:155]
	v_pk_mul_f32 v[82:83], v[82:83], v[156:157]
	v_rcp_f32_e32 v150, v41
	v_rcp_f32_e32 v151, v185
	v_rcp_f32_e32 v152, v186
	v_rcp_f32_e32 v153, v187
	v_rcp_f32_e32 v154, v193
	v_rcp_f32_e32 v155, v194
	v_rcp_f32_e32 v156, v195
	v_rcp_f32_e32 v157, v196
	v_add_f32_e32 v41, 1.0, v174
	v_add_f32_e32 v174, 1.0, v175
	v_add_f32_e32 v175, 1.0, v176
	v_add_f32_e32 v176, 1.0, v202
	v_add_f32_e32 v185, 1.0, v203
	v_add_f32_e32 v186, 1.0, v204
	v_add_f32_e32 v187, 1.0, v205
	v_add_f32_e32 v193, 1.0, v201
	v_cvt_pk_bf16_f32 v76, v76, v77
; __device__ __forceinline__ unsigned pk2(float lo, float hi) { f32x2_c v = {lo, hi}; return __builtin_bit_cast(unsigned, __builtin_convertvector(v, bf16x2_c)); }
; __device__ __forceinline__ float bf2f(unsigned short h) { return __uint_as_float(((unsigned)h) << 16); }
; __device__ __forceinline__ float silu_f(float x) { return x * __builtin_amdgcn_rcpf(1.f + __expf(-x)); }
; __device__ __forceinline__ void p2a_conv(const Args& A, int G) {
;     ...
;             for (int e = 0; e < 8; ++e) { const float a = bs[e] + w[0][e] * bf2f((unsigned short)r0[e]) + w[1][e] * bf2f((unsigned short)r1[e]) + w[2][e] * bf2f((unsigned short)r2[e]) + w[3][e] * bf2f((unsigned short)r3[e]); o[e] = silu_f(a); }
;             v4u pw; pw.x = pk2(o[0], o[1]); pw.y = pk2(o[2], o[3]); pw.z = pk2(o[4], o[5]); pw.w = pk2(o[6], o[7]);
;             *(v4u*)(XC + (size_t)(m0 + i) * 2048 + ch) = pw; r0 = r1; r1 = r2; r2 = r3; } }
;     }
	v_cvt_pk_bf16_f32 v77, v78, v79
	v_cvt_pk_bf16_f32 v78, v80, v81
	v_cvt_pk_bf16_f32 v79, v82, v83
	v_pk_mul_f32 v[80:81], v[84:85], v[142:143]
	v_pk_mul_f32 v[82:83], v[86:87], v[144:145]
	v_pk_mul_f32 v[84:85], v[88:89], v[146:147]
	v_pk_mul_f32 v[86:87], v[90:91], v[148:149]
	v_rcp_f32_e32 v88, v41
	v_rcp_f32_e32 v89, v174
	v_rcp_f32_e32 v90, v175
	v_rcp_f32_e32 v91, v176
	v_rcp_f32_e32 v142, v185
	v_rcp_f32_e32 v143, v186
	v_rcp_f32_e32 v144, v187
	v_rcp_f32_e32 v145, v193
	v_add_f32_e32 v41, 1.0, v177
	v_add_f32_e32 v146, 1.0, v178
	v_add_f32_e32 v147, 1.0, v179
	v_add_f32_e32 v148, 1.0, v180
	v_add_f32_e32 v149, 1.0, v181
	v_add_f32_e32 v174, 1.0, v182
	v_add_f32_e32 v175, 1.0, v183
	v_add_f32_e32 v176, 1.0, v184
	flat_store_dwordx4 v[74:75], v[76:79]
	v_cvt_pk_bf16_f32 v74, v80, v81
	v_cvt_pk_bf16_f32 v75, v82, v83
	v_cvt_pk_bf16_f32 v76, v84, v85
	v_cvt_pk_bf16_f32 v77, v86, v87
	v_pk_mul_f32 v[78:79], v[92:93], v[158:159]
	v_pk_mul_f32 v[80:81], v[94:95], v[160:161]
	v_pk_mul_f32 v[82:83], v[96:97], v[162:163]
	v_pk_mul_f32 v[84:85], v[98:99], v[164:165]
	v_rcp_f32_e32 v86, v41
	v_rcp_f32_e32 v87, v146
	v_rcp_f32_e32 v92, v147
	v_rcp_f32_e32 v93, v148
	v_rcp_f32_e32 v94, v149
	v_rcp_f32_e32 v95, v174
	v_rcp_f32_e32 v96, v175
	v_rcp_f32_e32 v97, v176
	v_add_f32_e32 v41, 1.0, v188
	v_add_f32_e32 v98, 1.0, v189
	v_add_f32_e32 v99, 1.0, v190
	v_add_f32_e32 v146, 1.0, v191
	v_add_f32_e32 v147, 1.0, v192
	v_add_f32_e32 v148, 1.0, v206
	v_add_f32_e32 v149, 1.0, v207
	v_add_f32_e32 v158, 1.0, v208
	flat_store_dwordx4 v[72:73], v[74:77]
	v_cvt_pk_bf16_f32 v72, v78, v79
	v_cvt_pk_bf16_f32 v73, v80, v81
	v_cvt_pk_bf16_f32 v74, v82, v83
	v_cvt_pk_bf16_f32 v75, v84, v85
	v_pk_mul_f32 v[76:77], v[100:101], v[166:167]
	v_pk_mul_f32 v[78:79], v[102:103], v[168:169]
	v_pk_mul_f32 v[80:81], v[104:105], v[170:171]
	v_pk_mul_f32 v[82:83], v[106:107], v[172:173]
	v_rcp_f32_e32 v84, v41
	v_rcp_f32_e32 v85, v98
	v_rcp_f32_e32 v98, v99
	v_rcp_f32_e32 v99, v146
	v_rcp_f32_e32 v100, v147
	v_rcp_f32_e32 v101, v148
	v_rcp_f32_e32 v102, v149
	v_rcp_f32_e32 v103, v158
	flat_store_dwordx4 v[70:71], v[72:75]
	v_cvt_pk_bf16_f32 v70, v76, v77
	v_cvt_pk_bf16_f32 v71, v78, v79
	v_cvt_pk_bf16_f32 v72, v80, v81
	v_cvt_pk_bf16_f32 v73, v82, v83
	v_pk_mul_f32 v[74:75], v[108:109], v[150:151]
	v_pk_mul_f32 v[76:77], v[110:111], v[152:153]
	v_pk_mul_f32 v[78:79], v[112:113], v[154:155]
	v_pk_mul_f32 v[80:81], v[114:115], v[156:157]
	flat_store_dwordx4 v[68:69], v[70:73]
	v_cvt_pk_bf16_f32 v68, v74, v75
	v_cvt_pk_bf16_f32 v69, v76, v77
	v_cvt_pk_bf16_f32 v70, v78, v79
	v_cvt_pk_bf16_f32 v71, v80, v81
	v_pk_mul_f32 v[72:73], v[116:117], v[88:89]
	v_pk_mul_f32 v[74:75], v[118:119], v[90:91]
	v_pk_mul_f32 v[76:77], v[120:121], v[142:143]
	v_pk_mul_f32 v[78:79], v[122:123], v[144:145]
	flat_store_dwordx4 v[66:67], v[68:71]
	v_cvt_pk_bf16_f32 v66, v72, v73
	v_cvt_pk_bf16_f32 v67, v74, v75
	v_cvt_pk_bf16_f32 v68, v76, v77
	v_cvt_pk_bf16_f32 v69, v78, v79
	v_pk_mul_f32 v[70:71], v[126:127], v[86:87]
	v_pk_mul_f32 v[72:73], v[128:129], v[92:93]
	v_pk_mul_f32 v[74:75], v[132:133], v[94:95]
	v_pk_mul_f32 v[76:77], v[136:137], v[96:97]
	flat_store_dwordx4 v[64:65], v[66:69]
	v_cvt_pk_bf16_f32 v64, v70, v71
	v_cvt_pk_bf16_f32 v65, v72, v73
	v_cvt_pk_bf16_f32 v66, v74, v75
	v_cvt_pk_bf16_f32 v67, v76, v77
	v_pk_mul_f32 v[68:69], v[130:131], v[84:85]
	v_pk_mul_f32 v[70:71], v[138:139], v[98:99]
	v_pk_mul_f32 v[72:73], v[140:141], v[100:101]
	v_pk_mul_f32 v[74:75], v[134:135], v[102:103]
	flat_store_dwordx4 v[62:63], v[64:67]
	v_cvt_pk_bf16_f32 v62, v68, v69
	v_cvt_pk_bf16_f32 v63, v70, v71
	v_cvt_pk_bf16_f32 v64, v72, v73
	v_cvt_pk_bf16_f32 v65, v74, v75
	flat_store_dwordx4 v[60:61], v[62:65]
	s_cbranch_scc0 .LBB0_603
	s_add_i32 s3, s3, s38
	s_cmpk_gt_i32 s3, 0xff
	v_add_u32_e32 v125, s0, v125
	s_cbranch_scc0 .LBB0_600
